# E25: E24 + P15 FULL attention tiles use packed subtract and a packed row-sum tree in the online softmax
# speedup vs baseline: 1.0087x; 1.0021x over previous
.LBB0_4417:
	ds_bpermute_b32 v78, v220, v3
	v_max_f32_e32 v3, v3, v3
	s_and_b64 vcc, exec, s[90:91]
	s_waitcnt lgkmcnt(0)
	v_max_f32_e32 v78, v78, v78
	v_max_f32_e32 v3, v3, v78
	ds_bpermute_b32 v78, v221, v3
	s_waitcnt lgkmcnt(0)
	v_max3_f32 v78, v4, v3, v78
	s_cbranch_vccz .Lmy_smw1_m
	v_pk_add_f32 v[196:197], v[196:197], v[78:79] op_sel_hi:[1,0] neg_lo:[0,1] neg_hi:[0,1]
	v_pk_add_f32 v[198:199], v[198:199], v[78:79] op_sel_hi:[1,0] neg_lo:[0,1] neg_hi:[0,1]
	v_pk_add_f32 v[200:201], v[200:201], v[78:79] op_sel_hi:[1,0] neg_lo:[0,1] neg_hi:[0,1]
	v_pk_add_f32 v[202:203], v[202:203], v[78:79] op_sel_hi:[1,0] neg_lo:[0,1] neg_hi:[0,1]
	v_pk_add_f32 v[204:205], v[204:205], v[78:79] op_sel_hi:[1,0] neg_lo:[0,1] neg_hi:[0,1]
	v_pk_add_f32 v[206:207], v[206:207], v[78:79] op_sel_hi:[1,0] neg_lo:[0,1] neg_hi:[0,1]
	v_pk_add_f32 v[208:209], v[208:209], v[78:79] op_sel_hi:[1,0] neg_lo:[0,1] neg_hi:[0,1]
	v_pk_add_f32 v[210:211], v[210:211], v[78:79] op_sel_hi:[1,0] neg_lo:[0,1] neg_hi:[0,1]
	v_exp_f32_e32 v230, v196
	v_exp_f32_e32 v231, v197
	v_exp_f32_e32 v232, v198
	v_exp_f32_e32 v234, v199
	v_exp_f32_e32 v233, v200
	v_exp_f32_e32 v235, v201
	v_exp_f32_e32 v236, v202
	v_exp_f32_e32 v237, v203
	v_exp_f32_e32 v3, v204
	v_exp_f32_e32 v103, v205
	v_exp_f32_e32 v212, v206
	v_exp_f32_e32 v224, v207
	v_exp_f32_e32 v223, v208
	v_exp_f32_e32 v225, v209
	v_exp_f32_e32 v228, v210
	v_exp_f32_e32 v229, v211
	s_nop 0
	v_pk_add_f32 v[82:83], v[224:225], v[228:229]
	v_pk_add_f32 v[84:85], v[230:231], v[232:233]
	v_pk_add_f32 v[82:83], v[82:83], v[84:85]
	v_pk_add_f32 v[84:85], v[234:235], v[236:237]
	v_pk_add_f32 v[82:83], v[82:83], v[84:85]
	v_add_f32_e32 v80, v82, v83
	v_add_f32_e32 v80, v3, v80
	v_add_f32_e32 v80, v103, v80
	v_add_f32_e32 v80, v212, v80
	v_add_f32_e32 v80, v223, v80
	s_branch .LBB0_4420
.Lmy_smw1_m:
	v_sub_f32_e32 v3, v196, v78
	v_sub_f32_e32 v79, v197, v78
	v_sub_f32_e32 v80, v198, v78
	v_sub_f32_e32 v81, v199, v78
	v_sub_f32_e32 v82, v200, v78
	v_sub_f32_e32 v83, v201, v78
	v_sub_f32_e32 v84, v202, v78
	v_sub_f32_e32 v85, v203, v78
	v_sub_f32_e32 v86, v204, v78
	v_sub_f32_e32 v87, v205, v78
	v_sub_f32_e32 v88, v206, v78
	v_sub_f32_e32 v89, v207, v78
	v_sub_f32_e32 v90, v208, v78
	v_sub_f32_e32 v91, v209, v78
	v_sub_f32_e32 v92, v210, v78
	v_sub_f32_e32 v93, v211, v78
	v_exp_f32_e32 v230, v3
	v_exp_f32_e32 v231, v79
	v_exp_f32_e32 v232, v80
	v_exp_f32_e32 v234, v81
	v_exp_f32_e32 v233, v82
	v_exp_f32_e32 v235, v83
	v_exp_f32_e32 v236, v84
	v_exp_f32_e32 v237, v85
	v_exp_f32_e32 v3, v86
	v_exp_f32_e32 v103, v87
	v_exp_f32_e32 v212, v88
	v_exp_f32_e32 v224, v89
	v_exp_f32_e32 v223, v90
	v_exp_f32_e32 v225, v91
	v_exp_f32_e32 v228, v92
	v_exp_f32_e32 v229, v93

.LBB0_4423:
	ds_bpermute_b32 v62, v220, v79
	v_max_f32_e32 v63, v79, v79
	s_and_b64 vcc, exec, s[90:91]
	s_waitcnt lgkmcnt(0)
	v_max_f32_e32 v62, v62, v62
	v_max_f32_e32 v62, v63, v62
	ds_bpermute_b32 v63, v221, v62
	s_waitcnt lgkmcnt(0)
	v_max3_f32 v79, v5, v62, v63
	s_cbranch_vccz .Lmy_smw2_m
	v_pk_add_f32 v[82:83], v[82:83], v[78:79] op_sel:[0,1] op_sel_hi:[1,1] neg_lo:[0,1] neg_hi:[0,1]
	v_pk_add_f32 v[84:85], v[84:85], v[78:79] op_sel:[0,1] op_sel_hi:[1,1] neg_lo:[0,1] neg_hi:[0,1]
	v_pk_add_f32 v[86:87], v[86:87], v[78:79] op_sel:[0,1] op_sel_hi:[1,1] neg_lo:[0,1] neg_hi:[0,1]
	v_pk_add_f32 v[88:89], v[88:89], v[78:79] op_sel:[0,1] op_sel_hi:[1,1] neg_lo:[0,1] neg_hi:[0,1]
	v_pk_add_f32 v[90:91], v[90:91], v[78:79] op_sel:[0,1] op_sel_hi:[1,1] neg_lo:[0,1] neg_hi:[0,1]
	v_pk_add_f32 v[92:93], v[92:93], v[78:79] op_sel:[0,1] op_sel_hi:[1,1] neg_lo:[0,1] neg_hi:[0,1]
	v_pk_add_f32 v[196:197], v[196:197], v[78:79] op_sel:[0,1] op_sel_hi:[1,1] neg_lo:[0,1] neg_hi:[0,1]
	v_pk_add_f32 v[198:199], v[198:199], v[78:79] op_sel:[0,1] op_sel_hi:[1,1] neg_lo:[0,1] neg_hi:[0,1]
	v_exp_f32_e32 v70, v82
	v_exp_f32_e32 v71, v83
	v_exp_f32_e32 v72, v84
	v_exp_f32_e32 v74, v85
	v_exp_f32_e32 v73, v86
	v_exp_f32_e32 v75, v87
	v_exp_f32_e32 v76, v88
	v_exp_f32_e32 v77, v89
	v_exp_f32_e32 v62, v90
	v_exp_f32_e32 v63, v91
	v_exp_f32_e32 v64, v92
	v_exp_f32_e32 v66, v93
	v_exp_f32_e32 v65, v196
	v_exp_f32_e32 v67, v197
	v_exp_f32_e32 v68, v198
	v_exp_f32_e32 v69, v199
	s_nop 0
	v_pk_add_f32 v[82:83], v[62:63], v[64:65]
	v_pk_add_f32 v[84:85], v[66:67], v[68:69]
	v_pk_add_f32 v[82:83], v[82:83], v[84:85]
	v_pk_add_f32 v[84:85], v[70:71], v[72:73]
	v_pk_add_f32 v[82:83], v[82:83], v[84:85]
	v_pk_add_f32 v[84:85], v[74:75], v[76:77]
	v_pk_add_f32 v[82:83], v[82:83], v[84:85]
	v_add_f32_e32 v81, v82, v83
	s_branch .LBB0_4426
.Lmy_smw2_m:
	v_sub_f32_e32 v62, v82, v79
	v_sub_f32_e32 v63, v83, v79
	v_sub_f32_e32 v64, v84, v79
	v_sub_f32_e32 v65, v85, v79
	v_sub_f32_e32 v66, v86, v79
	v_sub_f32_e32 v67, v87, v79
	v_sub_f32_e32 v68, v88, v79
	v_sub_f32_e32 v69, v89, v79
	v_sub_f32_e32 v81, v90, v79
	v_sub_f32_e32 v200, v91, v79
	v_sub_f32_e32 v201, v92, v79
	v_sub_f32_e32 v202, v93, v79
	v_sub_f32_e32 v203, v196, v79
	v_sub_f32_e32 v204, v197, v79
	v_sub_f32_e32 v205, v198, v79
	v_sub_f32_e32 v206, v199, v79
	v_exp_f32_e32 v70, v62
	v_exp_f32_e32 v71, v63
	v_exp_f32_e32 v72, v64
	v_exp_f32_e32 v74, v65
	v_exp_f32_e32 v73, v66
	v_exp_f32_e32 v75, v67
	v_exp_f32_e32 v76, v68
	v_exp_f32_e32 v77, v69
	v_exp_f32_e32 v62, v81
	v_exp_f32_e32 v63, v200
	v_exp_f32_e32 v64, v201
	v_exp_f32_e32 v66, v202
	v_exp_f32_e32 v65, v203
	v_exp_f32_e32 v67, v204
	v_exp_f32_e32 v68, v205
	v_exp_f32_e32 v69, v206

.LBB0_4447:
	ds_bpermute_b32 v3, v220, v103
	v_max_f32_e32 v78, v103, v103
	s_and_b64 vcc, exec, s[38:39]
	s_waitcnt lgkmcnt(0)
	v_max_f32_e32 v3, v3, v3
	v_max_f32_e32 v3, v78, v3
	ds_bpermute_b32 v78, v221, v3
	s_waitcnt lgkmcnt(0)
	v_max3_f32 v78, v4, v3, v78
	s_cbranch_vccz .Lmy_sms1_m
	v_sub_f32_e32 v3, v90, v78
	v_pk_add_f32 v[196:197], v[196:197], v[78:79] op_sel_hi:[1,0] neg_lo:[0,1] neg_hi:[0,1]
	v_sub_f32_e32 v81, v93, v78
	v_pk_add_f32 v[198:199], v[198:199], v[78:79] op_sel_hi:[1,0] neg_lo:[0,1] neg_hi:[0,1]
	v_pk_add_f32 v[200:201], v[200:201], v[78:79] op_sel_hi:[1,0] neg_lo:[0,1] neg_hi:[0,1]
	v_pk_add_f32 v[202:203], v[202:203], v[78:79] op_sel_hi:[1,0] neg_lo:[0,1] neg_hi:[0,1]
	v_pk_add_f32 v[204:205], v[204:205], v[78:79] op_sel_hi:[1,0] neg_lo:[0,1] neg_hi:[0,1]
	v_pk_add_f32 v[206:207], v[206:207], v[78:79] op_sel_hi:[1,0] neg_lo:[0,1] neg_hi:[0,1]
	v_pk_add_f32 v[208:209], v[208:209], v[78:79] op_sel_hi:[1,0] neg_lo:[0,1] neg_hi:[0,1]
	v_exp_f32_e32 v228, v3
	v_exp_f32_e32 v229, v196
	v_exp_f32_e32 v230, v197
	v_exp_f32_e32 v232, v81
	v_exp_f32_e32 v231, v198
	v_exp_f32_e32 v233, v199
	v_exp_f32_e32 v234, v200
	v_exp_f32_e32 v235, v201
	v_exp_f32_e32 v3, v202
	v_exp_f32_e32 v103, v203
	v_exp_f32_e32 v210, v204
	v_exp_f32_e32 v212, v205
	v_exp_f32_e32 v211, v206
	v_exp_f32_e32 v223, v207
	v_exp_f32_e32 v224, v208
	v_exp_f32_e32 v225, v209
	s_nop 0
	v_pk_add_f32 v[82:83], v[210:211], v[224:225]
	v_pk_add_f32 v[84:85], v[228:229], v[230:231]
	v_pk_add_f32 v[82:83], v[82:83], v[84:85]
	v_pk_add_f32 v[84:85], v[232:233], v[234:235]
	v_pk_add_f32 v[82:83], v[82:83], v[84:85]
	v_add_f32_e32 v80, v82, v83
	v_add_f32_e32 v80, v3, v80
	v_add_f32_e32 v80, v103, v80
	v_add_f32_e32 v80, v212, v80
	v_add_f32_e32 v80, v223, v80
	s_branch .LBB0_4450
.Lmy_sms1_m:
	v_sub_f32_e32 v3, v90, v78
	v_sub_f32_e32 v79, v196, v78
	v_sub_f32_e32 v80, v197, v78
	v_sub_f32_e32 v81, v93, v78
	v_sub_f32_e32 v82, v198, v78
	v_sub_f32_e32 v83, v199, v78
	v_sub_f32_e32 v84, v200, v78
	v_sub_f32_e32 v85, v201, v78
	v_sub_f32_e32 v86, v202, v78
	v_sub_f32_e32 v87, v203, v78
	v_sub_f32_e32 v88, v204, v78
	v_sub_f32_e32 v89, v205, v78
	v_sub_f32_e32 v91, v206, v78
	v_sub_f32_e32 v92, v207, v78
	v_sub_f32_e32 v224, v208, v78
	v_sub_f32_e32 v225, v209, v78
	v_exp_f32_e32 v228, v3
	v_exp_f32_e32 v229, v79
	v_exp_f32_e32 v230, v80
	v_exp_f32_e32 v232, v81
	v_exp_f32_e32 v231, v82
	v_exp_f32_e32 v233, v83
	v_exp_f32_e32 v234, v84
	v_exp_f32_e32 v235, v85
	v_exp_f32_e32 v3, v86
	v_exp_f32_e32 v103, v87
	v_exp_f32_e32 v210, v88
	v_exp_f32_e32 v212, v89
	v_exp_f32_e32 v211, v91
	v_exp_f32_e32 v223, v92
	v_exp_f32_e32 v224, v224
	v_exp_f32_e32 v225, v225

.LBB0_4453:
	ds_bpermute_b32 v62, v220, v81
	v_max_f32_e32 v63, v81, v81
	s_and_b64 vcc, exec, s[38:39]
	s_waitcnt lgkmcnt(0)
	v_max_f32_e32 v62, v62, v62
	v_max_f32_e32 v62, v63, v62
	ds_bpermute_b32 v63, v221, v62
	s_waitcnt lgkmcnt(0)
	v_max3_f32 v79, v5, v62, v63
	s_cbranch_vccz .Lmy_sms2_m
	v_sub_f32_e32 v62, v74, v79
	v_pk_add_f32 v[82:83], v[82:83], v[78:79] op_sel:[0,1] op_sel_hi:[1,1] neg_lo:[0,1] neg_hi:[0,1]
	v_sub_f32_e32 v65, v77, v79
	v_pk_add_f32 v[84:85], v[84:85], v[78:79] op_sel:[0,1] op_sel_hi:[1,1] neg_lo:[0,1] neg_hi:[0,1]
	v_pk_add_f32 v[86:87], v[86:87], v[78:79] op_sel:[0,1] op_sel_hi:[1,1] neg_lo:[0,1] neg_hi:[0,1]
	v_pk_add_f32 v[88:89], v[88:89], v[78:79] op_sel:[0,1] op_sel_hi:[1,1] neg_lo:[0,1] neg_hi:[0,1]
	v_pk_add_f32 v[90:91], v[90:91], v[78:79] op_sel:[0,1] op_sel_hi:[1,1] neg_lo:[0,1] neg_hi:[0,1]
	v_pk_add_f32 v[92:93], v[92:93], v[78:79] op_sel:[0,1] op_sel_hi:[1,1] neg_lo:[0,1] neg_hi:[0,1]
	v_pk_add_f32 v[196:197], v[196:197], v[78:79] op_sel:[0,1] op_sel_hi:[1,1] neg_lo:[0,1] neg_hi:[0,1]
	v_exp_f32_e32 v70, v62
	v_exp_f32_e32 v71, v82
	v_exp_f32_e32 v72, v83
	v_exp_f32_e32 v75, v65
	v_exp_f32_e32 v73, v84
	v_exp_f32_e32 v76, v85
	v_exp_f32_e32 v198, v86
	v_exp_f32_e32 v199, v87
	v_exp_f32_e32 v62, v88
	v_exp_f32_e32 v63, v89
	v_exp_f32_e32 v64, v90
	v_exp_f32_e32 v66, v91
	v_exp_f32_e32 v65, v92
	v_exp_f32_e32 v67, v93
	v_exp_f32_e32 v68, v196
	v_exp_f32_e32 v69, v197
	s_nop 0
	v_pk_add_f32 v[82:83], v[62:63], v[64:65]
	v_pk_add_f32 v[84:85], v[66:67], v[68:69]
	v_pk_add_f32 v[82:83], v[82:83], v[84:85]
	v_pk_add_f32 v[84:85], v[70:71], v[72:73]
	v_pk_add_f32 v[82:83], v[82:83], v[84:85]
	v_pk_add_f32 v[82:83], v[82:83], v[198:199]
	v_add_f32_e32 v81, v82, v83
	v_add_f32_e32 v81, v75, v81
	v_add_f32_e32 v81, v76, v81
	s_branch .LBB0_4456
.Lmy_sms2_m:
	v_sub_f32_e32 v62, v74, v79
	v_sub_f32_e32 v63, v82, v79
	v_sub_f32_e32 v64, v83, v79
	v_sub_f32_e32 v65, v77, v79
	v_sub_f32_e32 v66, v84, v79
	v_sub_f32_e32 v67, v85, v79
	v_sub_f32_e32 v68, v86, v79
	v_sub_f32_e32 v69, v87, v79
	v_sub_f32_e32 v81, v88, v79
	v_sub_f32_e32 v200, v89, v79
	v_sub_f32_e32 v201, v90, v79
	v_sub_f32_e32 v202, v91, v79
	v_sub_f32_e32 v203, v92, v79
	v_sub_f32_e32 v204, v93, v79
	v_sub_f32_e32 v205, v196, v79
	v_sub_f32_e32 v206, v197, v79
	v_exp_f32_e32 v70, v62
	v_exp_f32_e32 v71, v63
	v_exp_f32_e32 v72, v64
	v_exp_f32_e32 v75, v65
	v_exp_f32_e32 v73, v66
	v_exp_f32_e32 v76, v67
	v_exp_f32_e32 v198, v68
	v_exp_f32_e32 v199, v69
	v_exp_f32_e32 v62, v81
	v_exp_f32_e32 v63, v200
	v_exp_f32_e32 v64, v201
	v_exp_f32_e32 v66, v202
	v_exp_f32_e32 v65, v203
	v_exp_f32_e32 v67, v204
	v_exp_f32_e32 v68, v205
	v_exp_f32_e32 v69, v206
